# hyena item prologue: first-chunk U loads issued before the G-build krev wait (order 0 and 1)
# speedup vs baseline: 1.0031x; 1.0031x over previous
.LBB0_647:
	s_and_b64 vcc, exec, s[18:19]
	s_cbranch_vccz .LBB0_685
	s_add_i32 s0, s10, s34
	s_ashr_i32 s1, s0, 31
	s_lshl_b64 s[0:1], s[0:1], 2
	v_readlane_b32 s4, v254, 4
	s_add_u32 s0, s4, s0
	v_readlane_b32 s4, v254, 5
	s_addc_u32 s1, s4, s1
	global_load_dword v57, v1, s[0:1]
	s_lshl_b32 s0, s35, 6
	s_and_b32 s12, s0, 0x600
	v_mov_b32_e32 v61, v211
	s_movk_i32 s0, 0x140
	s_waitcnt lgkmcnt(0)
	v_cmp_gt_i32_e32 vcc, s0, v61
	v_lshlrev_b32_e32 v10, 3, v61
	s_barrier
	s_lshl_b64 s[0:1], s[6:7], 1
	v_readlane_b32 s18, v253, 54
	v_readlane_b32 s19, v253, 55
	s_add_u32 s0, s18, s0
	v_and_b32_e32 v75, 0xf8, v10
	s_addc_u32 s1, s19, s1
	v_lshlrev_b32_e32 v0, 1, v75
	v_lshl_add_u64 v[2:3], s[0:1], 0, v[0:1]
	v_ashrrev_i32_e32 v0, 5, v61
	s_movk_i32 s4, 0x1200
	v_mad_i64_i32 v[4:5], s[0:1], v0, s4, v[2:3]
	global_load_dwordx4 v[48:51], v[4:5], off offset:512
	v_cmp_ne_u32_e64 s[18:19], 0, v75
	v_mov_b32_e32 v77, 0
	v_mov_b32_e32 v76, 0
	s_and_saveexec_b64 s[0:1], s[18:19]
	s_cbranch_execz .LBB0_656
	global_load_ushort v76, v[4:5], off offset:510
.LBB0_656:
	s_or_b64 exec, exec, s[0:1]
	v_add_u32_e32 v6, 0x200, v61
	v_ashrrev_i32_e32 v6, 5, v6
	v_mad_i64_i32 v[2:3], s[0:1], v6, s4, v[2:3]
	global_load_ushort v78, v[4:5], off offset:528
	global_load_dwordx4 v[52:55], v[2:3], off offset:512
	s_and_saveexec_b64 s[0:1], s[18:19]
	s_cbranch_execz .LBB0_658
	global_load_ushort v77, v[2:3], off offset:510
.LBB0_658:
	s_or_b64 exec, exec, s[0:1]
	global_load_ushort v82, v[2:3], off offset:528
	s_movk_i32 s0, 0x140
	v_cmp_gt_i32_e32 vcc, s0, v61
	s_and_saveexec_b64 s[10:11], vcc
	s_cbranch_execz .LBB0_654
	s_lshl_b64 s[0:1], s[8:9], 13
	v_readlane_b32 s4, v254, 8
	v_subrev_u32_e32 v8, s12, v10
	s_add_u32 s8, s4, s0
	v_readlane_b32 s0, v254, 9
	v_add_u32_e32 v0, 0x5f8, v8
	s_addc_u32 s9, s0, s1
	v_cmp_lt_i32_e32 vcc, 0, v61
	v_cmp_lt_i32_e64 s[0:1], -1, v0
	v_mov_b32_e32 v6, 0
	s_and_b64 s[18:19], vcc, s[0:1]
	v_mov_b32_e32 v2, 0
	v_mov_b32_e32 v3, 0
	v_mov_b32_e32 v4, 0
	v_mov_b32_e32 v5, 0
	s_and_saveexec_b64 s[0:1], s[18:19]
	s_cbranch_execz .LBB0_651
	v_ashrrev_i32_e32 v9, 31, v8
	v_lshl_add_u64 v[2:3], v[8:9], 1, s[8:9]
	global_load_dwordx4 v[2:5], v[2:3], off offset:3056

.LBB0_654:
	s_or_b64 exec, exec, s[10:11]
	s_lshl_b64 s[0:1], s[6:7], 1
	v_readlane_b32 s8, v253, 54
	v_readlane_b32 s9, v253, 55
	s_add_u32 s0, s8, s0
	s_addc_u32 s1, s9, s1
	v_ashrrev_i32_e32 v0, 5, v61
	s_movk_i32 s4, 0x1200
	v_add_u32_e32 v6, 0x200, v61
	v_ashrrev_i32_e32 v6, 5, v6
	v_bfe_u32 v74, v61, 5, 1
	v_and_b32_e32 v4, 7, v61
	v_mad_i64_i32 v[68:69], s[8:9], v0, s4, 0
	v_and_b32_e32 v3, 0x7fffffd8, v61
	v_mul_u32_u24_e32 v4, 0x1420, v4
	v_mul_lo_u32 v17, v0, s60
	v_lshlrev_b32_e32 v0, 4, v74
	v_lshlrev_b32_e32 v81, 4, v61
	v_or_b32_e32 v4, v4, v0
	v_lshlrev_b32_e32 v3, 1, v3
	v_mad_i64_i32 v[70:71], s[8:9], v6, s4, 0
	v_and_b32_e32 v79, 31, v61
	v_and_b32_e32 v2, 0x1f0, v81
	v_sub_u32_e32 v3, v4, v3
	v_readlane_b32 s4, v254, 38
	v_add_u32_e32 v16, 0, v2
	v_mul_u32_u24_e32 v2, 0x210, v79
	s_waitcnt vmcnt(15)
	v_mul_lo_u32 v18, v6, s60
	v_add_u32_e32 v83, s4, v3
	v_readlane_b32 s4, v254, 37
	v_mov_b32_e32 v14, v1
	v_mov_b32_e32 v15, v1
	v_add3_u32 v84, v2, v0, s4
	v_mov_b32_e32 v0, v1
	v_mov_b32_e32 v2, v1
	v_mov_b32_e32 v3, v1
	v_mov_b32_e32 v4, v1
	v_mov_b32_e32 v5, v1
	v_mov_b32_e32 v6, v1
	v_mov_b32_e32 v7, v1
	v_mov_b32_e32 v8, v1
	v_mov_b32_e32 v9, v1
	v_mov_b32_e32 v10, v1
	v_mov_b32_e32 v11, v1
	v_mov_b32_e32 v12, v1
	v_mov_b32_e32 v13, v1
	v_add_u32_e32 v85, v16, v17
	v_add_u32_e32 v86, v16, v18
	s_waitcnt vmcnt(14)
	v_mov_b64_e32 v[30:31], v[14:15]
	v_mov_b64_e32 v[46:47], v[14:15]
	v_and_b32_e32 v80, 63, v61
	s_waitcnt vmcnt(11)
	v_mov_b32_e32 v66, v63
	v_mov_b32_e32 v67, v62
	v_mov_b32_e32 v64, v63
	s_mov_b32 s10, 0
	v_mov_b64_e32 v[28:29], v[12:13]
	v_mov_b64_e32 v[26:27], v[10:11]
	v_mov_b64_e32 v[24:25], v[8:9]
	v_mov_b64_e32 v[22:23], v[6:7]
	v_mov_b64_e32 v[20:21], v[4:5]
	v_mov_b64_e32 v[18:19], v[2:3]
	v_mov_b64_e32 v[16:17], v[0:1]
	v_mov_b64_e32 v[44:45], v[12:13]
	v_mov_b64_e32 v[42:43], v[10:11]
	v_mov_b64_e32 v[40:41], v[8:9]
	v_mov_b64_e32 v[38:39], v[6:7]
	v_mov_b64_e32 v[36:37], v[4:5]
	v_mov_b64_e32 v[34:35], v[2:3]
	v_mov_b64_e32 v[32:33], v[0:1]

.LBB0_869:
	s_and_b64 vcc, exec, s[10:11]
	s_cbranch_vccz .LBB0_903
	s_add_i32 s0, s88, s0
	s_ashr_i32 s1, s0, 31
	s_lshl_b64 s[0:1], s[0:1], 2
	v_readlane_b32 s4, v254, 4
	s_add_u32 s0, s4, s0
	v_readlane_b32 s4, v254, 5
	s_addc_u32 s1, s4, s1
	global_load_dword v43, v1, s[0:1]
	v_mov_b32_e32 v46, v211
	s_movk_i32 s0, 0x13f
	s_nop 0
	v_cmp_lt_i32_e32 vcc, s0, v46
	s_waitcnt vmcnt(10)
	v_lshlrev_b32_e32 v59, 4, v46
	s_barrier
	s_lshl_b64 s[0:1], s[6:7], 1
	v_readlane_b32 s4, v254, 2
	v_readlane_b32 s5, v254, 3
	s_add_u32 s0, s4, s0
	v_lshlrev_b32_e32 v0, 3, v46
	s_addc_u32 s1, s5, s1
	v_and_b32_e32 v0, 0xf8, v0
	v_lshlrev_b32_e32 v0, 1, v0
	v_lshl_add_u64 v[48:49], s[0:1], 0, v[0:1]
	v_ashrrev_i32_e32 v244, 5, v46
	s_movk_i32 s4, 0x1200
	v_add_u32_e32 v0, 0x200, v46
	v_mad_i64_i32 v[54:55], s[0:1], v244, s4, v[48:49]
	v_ashrrev_i32_e32 v245, 5, v0
	v_mad_i64_i32 v[56:57], s[0:1], v245, s4, v[48:49]
	global_load_dwordx4 v[236:239], v[54:55], off offset:512
	global_load_dwordx4 v[240:243], v[56:57], off offset:512
	s_and_saveexec_b64 s[0:1], vcc
	s_xor_b64 s[0:1], exec, s[0:1]
	v_lshlrev_b32_e32 v59, 4, v46
	s_or_saveexec_b64 s[10:11], s[0:1]
	s_lshl_b32 s0, s90, 6
	s_and_b32 s12, s0, 0x600
	v_lshlrev_b32_e32 v10, 3, v46
	s_xor_b64 exec, exec, s[10:11]
	s_cbranch_execz .LBB0_878
	s_lshl_b64 s[0:1], s[8:9], 13
	v_readlane_b32 s4, v254, 8
	v_subrev_u32_e32 v8, s12, v10
	s_add_u32 s8, s4, s0
	v_readlane_b32 s0, v254, 9
	v_add_u32_e32 v0, 0x5f8, v8
	s_addc_u32 s9, s0, s1
	v_cmp_lt_i32_e32 vcc, 0, v46
	v_cmp_lt_i32_e64 s[0:1], -1, v0
	v_mov_b32_e32 v6, 0
	s_and_b64 s[14:15], vcc, s[0:1]
	v_mov_b32_e32 v2, 0
	v_mov_b32_e32 v3, 0
	v_mov_b32_e32 v4, 0
	v_mov_b32_e32 v5, 0
	s_and_saveexec_b64 s[0:1], s[14:15]
	s_cbranch_execz .LBB0_875
	v_ashrrev_i32_e32 v9, 31, v8
	v_lshl_add_u64 v[2:3], v[8:9], 1, s[8:9]
	global_load_dwordx4 v[2:5], v[2:3], off offset:3056

.LBB0_878:
	s_or_b64 exec, exec, s[10:11]
	v_ashrrev_i32_e32 v10, 5, v46
	s_movk_i32 s4, 0x1200
	v_add_u32_e32 v0, 0x200, v46
	v_ashrrev_i32_e32 v11, 5, v0
	v_and_b32_e32 v0, 0x1f0, v59
	v_add_u32_e32 v0, 0, v0
	v_mul_lo_u32 v12, v10, s60
	v_add_u32_e32 v63, v0, v12
	v_mul_lo_u32 v12, v11, s60
	v_add_u32_e32 v64, v0, v12
	s_waitcnt lgkmcnt(0)
	s_barrier
	s_waitcnt vmcnt(8)
	v_bfe_u32 v60, v46, 5, 1
	v_mad_i64_i32 v[52:53], s[0:1], v10, s4, 0
	v_mad_i64_i32 v[50:51], s[0:1], v11, s4, 0
	v_and_b32_e32 v0, 31, v46
	v_readlane_b32 s0, v254, 38
	v_and_b32_e32 v61, 63, v46
	s_waitcnt vmcnt(1)
	ds_write_b128 v63, v[236:239] offset:41216
	s_waitcnt vmcnt(0)
	ds_write_b128 v64, v[240:243] offset:41216
	s_waitcnt lgkmcnt(0)
	s_barrier
	global_load_dwordx4 v[34:37], v[54:55], off offset:1024
	global_load_dwordx4 v[38:41], v[56:57], off offset:1024
	v_and_b32_e32 v4, 7, v46
	v_and_b32_e32 v3, 0x7fffffd8, v46
	v_mul_u32_u24_e32 v4, 0x1420, v4
	v_lshlrev_b32_e32 v5, 4, v60
	v_or_b32_e32 v4, v4, v5
	v_lshlrev_b32_e32 v3, 1, v3
	v_sub_u32_e32 v65, v4, v3
	v_mul_u32_u24_e32 v2, 0x210, v0
	v_add_u32_e32 v66, s0, v65
	v_readlane_b32 s0, v254, 37
	s_nop 1
	v_add3_u32 v62, v2, v5, s0
	v_mov_b32_e32 v2, 0
	s_mov_b32 s0, 0
	v_mov_b32_e32 v3, v2
	v_mov_b32_e32 v4, v2
	v_mov_b32_e32 v5, v2
	v_mov_b32_e32 v6, v2
	v_mov_b32_e32 v7, v2
	v_mov_b32_e32 v8, v2
	v_mov_b32_e32 v9, v2
	v_mov_b32_e32 v10, v2
	v_mov_b32_e32 v11, v2
	v_mov_b32_e32 v12, v2
	v_mov_b32_e32 v13, v2
	v_mov_b32_e32 v14, v2
	v_mov_b32_e32 v15, v2
	v_mov_b32_e32 v16, v2
	v_mov_b32_e32 v17, v2
	v_mov_b32_e32 v18, v2
	v_mov_b32_e32 v19, v2
	v_mov_b32_e32 v20, v2
	v_mov_b32_e32 v21, v2
	v_mov_b32_e32 v22, v2
	v_mov_b32_e32 v23, v2
	v_mov_b32_e32 v24, v2
	v_mov_b32_e32 v25, v2
	v_mov_b32_e32 v26, v2
	v_mov_b32_e32 v27, v2
	v_mov_b32_e32 v28, v2
	v_mov_b32_e32 v29, v2
	v_mov_b32_e32 v30, v2
	v_mov_b32_e32 v31, v2
	v_mov_b32_e32 v32, v2
	v_mov_b32_e32 v33, v2
